# v90 with the K-loop trailing barrier hoisted above the last 8 MFMAs instead of 4 (priority-2 tail)
# baseline (speedup 1.0000x reference)
; #define PG8_STAGE(bufoff, gbase, voff) do { _Pragma("unroll") for (int _i = 0; _i < 2; ++_i) \
;         __builtin_amdgcn_global_load_lds((const unsigned*)((const char*)(gbase) + (voff)[_i]), (PG8_LAS unsigned*)(lds + (bufoff) + ldsw + _i * 8192), 16, 0, 0); } while (0)
; #define PG8_LDA(dst, b, h) do { _Pragma("unroll") for (int m = 0; m < 4; ++m) _Pragma("unroll") for (int k = 0; k < 2; ++k) dst[m][k] = *(const PG8_LAS bf16x8*)(lds + PG8_SA(b, h) + aoff + m * 2048 + k * 1024); } while (0)
; #define PG8_LDB(dst, b, h) do { _Pragma("unroll") for (int n = 0; n < 2; ++n) _Pragma("unroll") for (int k = 0; k < 2; ++k) dst[n][k] = *(const PG8_LAS bf16x8*)(lds + PG8_SB(b, h) + boff + n * 2048 + k * 1024); } while (0)
; #define PG8_MMA(ai, bj, At, Bt) do { __builtin_amdgcn_s_setprio(1); _Pragma("unroll") for (int m = 0; m < 4; ++m) _Pragma("unroll") for (int n = 0; n < 2; ++n) _Pragma("unroll") for (int k = 0; k < 2; ++k) \
;         acc[ai][bj][m][n] = __builtin_amdgcn_mfma_f32_16x16x32_bf16(Bt[n][k], At[m][k], acc[ai][bj][m][n], 0, 0, 0); __builtin_amdgcn_s_setprio(0); } while (0)
; #define PG8_WAIT_V(n) asm volatile("s_waitcnt vmcnt(" #n ")" ::: "memory")
; #define PG8_WAIT_L(n) asm volatile("s_waitcnt lgkmcnt(" #n ")" ::: "memory")
; #define PG8_BAR __builtin_amdgcn_s_barrier()
; #define PG8_SCHED __builtin_amdgcn_sched_barrier(0)
; template <class Epi, class Sched, bool ALIGN_EPI = false, bool SP2 = false>
; __device__ __forceinline__ void gemm_phase(PG8_LAS unsigned char* lds, const Gemm g, const Sched& S, const Epi& E) {
;     ...
;             PG8_LDB(B0, 0, 0); PG8_LDB(B1, 0, 1); PG8_SCHED; PG8_LDA(At, 0, 0); PG8_STAGE(PG8_SA(1, 1), a1 + hstep, voffA);
;             PG8_WAIT_V(8); PG8_WAIT_L(0); PG8_BAR; PG8_MMA(0, 0, At, B0); PG8_MMA(0, 1, At, B1); PG8_BAR; PG8_SCHED;
;             PG8_LDA(At, 0, 1); PG8_STAGE(PG8_SB(0, 0), b2, voffB); PG8_STAGE(PG8_SB(0, 1), b2 + hstep, voffB); PG8_STAGE(PG8_SA(0, 0), a2, voffA);
;             PG8_WAIT_V(8); PG8_WAIT_L(0); PG8_BAR; PG8_MMA(1, 0, At, B0); PG8_MMA(1, 1, At, B1); PG8_BAR; PG8_SCHED;
.LBB0_274:
	s_add_u32 s22, s20, 0xfffc0080
	s_addc_u32 s23, s21, -1
	s_add_i32 s39, 0, 0x10000
	s_cmp_eq_u32 s38, 12
	s_cselect_b32 s25, s5, s23
	s_cselect_b32 s24, s13, s22
	v_add_u32_e32 v148, s39, v151
	s_cselect_b32 s23, s11, s37
	s_cselect_b32 s22, s35, s36
	s_add_i32 s45, 0, 0x14000
	ds_read_b128 v[140:143], v148
	ds_read_b128 v[144:147], v148 offset:1024
	ds_read_b128 v[156:159], v148 offset:2048
	ds_read_b128 v[160:163], v148 offset:3072
	v_add_u32_e32 v148, s45, v151
	ds_read_b128 v[164:167], v148
	ds_read_b128 v[168:171], v148 offset:1024
	ds_read_b128 v[182:185], v148 offset:2048
	ds_read_b128 v[186:189], v148 offset:3072
	v_lshl_add_u64 v[148:149], s[20:21], 0, v[136:137]
	s_add_i32 m0, s19, 0xc000
	ds_read_b128 v[190:193], v154
	ds_read_b128 v[194:197], v154 offset:1024
	ds_read_b128 v[198:201], v154 offset:2048
	ds_read_b128 v[202:205], v154 offset:3072
	ds_read_b128 v[228:231], v154 offset:4096
	ds_read_b128 v[236:239], v154 offset:5120
	ds_read_b128 v[240:243], v154 offset:6144
	ds_read_b128 v[244:247], v154 offset:7168
	global_load_lds_dwordx4 v[148:149], off
	v_lshl_add_u64 v[148:149], s[20:21], 0, v[138:139]
	s_add_i32 m0, s19, 0xe000
	s_nop 0
	global_load_lds_dwordx4 v[148:149], off
	s_waitcnt vmcnt(8)
	s_waitcnt lgkmcnt(0)
	s_barrier
	s_setprio 1
	s_waitcnt lgkmcnt(0)
	v_mfma_f32_16x16x32_bf16 v[124:127], v[140:143], v[190:193], v[124:127]
	v_mfma_f32_16x16x32_bf16 v[120:123], v[156:159], v[190:193], v[120:123]
	v_mfma_f32_16x16x32_bf16 v[108:111], v[140:143], v[198:201], v[108:111]
	v_mfma_f32_16x16x32_bf16 v[104:107], v[156:159], v[198:201], v[104:107]
	v_mfma_f32_16x16x32_bf16 v[92:95], v[140:143], v[228:231], v[92:95]
	v_mfma_f32_16x16x32_bf16 v[88:91], v[156:159], v[228:231], v[88:91]
	v_mfma_f32_16x16x32_bf16 v[76:79], v[140:143], v[240:243], v[76:79]
	v_mfma_f32_16x16x32_bf16 v[72:75], v[156:159], v[240:243], v[72:75]
	v_mfma_f32_16x16x32_bf16 v[124:127], v[144:147], v[194:197], v[124:127]
	v_mfma_f32_16x16x32_bf16 v[120:123], v[160:163], v[194:197], v[120:123]
	v_mfma_f32_16x16x32_bf16 v[108:111], v[144:147], v[202:205], v[108:111]
	v_mfma_f32_16x16x32_bf16 v[104:107], v[160:163], v[202:205], v[104:107]
	v_mfma_f32_16x16x32_bf16 v[92:95], v[144:147], v[236:239], v[92:95]
	v_mfma_f32_16x16x32_bf16 v[88:91], v[160:163], v[236:239], v[88:91]
	v_mfma_f32_16x16x32_bf16 v[76:79], v[144:147], v[244:247], v[76:79]
	v_mfma_f32_16x16x32_bf16 v[72:75], v[160:163], v[244:247], v[72:75]
	s_setprio 0
	s_setprio 1
	v_mfma_f32_16x16x32_bf16 v[116:119], v[164:167], v[190:193], v[116:119]
	v_mfma_f32_16x16x32_bf16 v[112:115], v[182:185], v[190:193], v[112:115]
	v_mfma_f32_16x16x32_bf16 v[100:103], v[164:167], v[198:201], v[100:103]
	v_mfma_f32_16x16x32_bf16 v[96:99], v[182:185], v[198:201], v[96:99]
	v_mfma_f32_16x16x32_bf16 v[84:87], v[164:167], v[228:231], v[84:87]
	v_mfma_f32_16x16x32_bf16 v[80:83], v[182:185], v[228:231], v[80:83]
	v_mfma_f32_16x16x32_bf16 v[68:71], v[164:167], v[240:243], v[68:71]
	v_mfma_f32_16x16x32_bf16 v[64:67], v[182:185], v[240:243], v[64:67]
	s_setprio 2
	s_barrier
	v_mfma_f32_16x16x32_bf16 v[116:119], v[168:171], v[194:197], v[116:119]
	v_mfma_f32_16x16x32_bf16 v[112:115], v[186:189], v[194:197], v[112:115]
	v_mfma_f32_16x16x32_bf16 v[100:103], v[168:171], v[202:205], v[100:103]
	v_mfma_f32_16x16x32_bf16 v[96:99], v[186:189], v[202:205], v[96:99]
	v_mfma_f32_16x16x32_bf16 v[84:87], v[168:171], v[236:239], v[84:87]
	v_mfma_f32_16x16x32_bf16 v[80:83], v[186:189], v[236:239], v[80:83]
	v_mfma_f32_16x16x32_bf16 v[68:71], v[168:171], v[244:247], v[68:71]
	v_mfma_f32_16x16x32_bf16 v[64:67], v[186:189], v[244:247], v[64:67]
	s_setprio 0
	s_add_i32 s39, s39, s26
	v_lshl_add_u64 v[148:149], s[22:23], 0, v[130:131]
	s_mov_b32 m0, s39
	ds_read_b128 v[190:193], v154 offset:16384
	ds_read_b128 v[194:197], v154 offset:17408
	ds_read_b128 v[198:201], v154 offset:18432
	ds_read_b128 v[202:205], v154 offset:19456
	ds_read_b128 v[228:231], v154 offset:20480
	ds_read_b128 v[236:239], v154 offset:21504
	ds_read_b128 v[240:243], v154 offset:22528
	ds_read_b128 v[244:247], v154 offset:23552
	global_load_lds_dwordx4 v[148:149], off
	s_add_i32 m0, s39, 0x2000
	s_add_u32 s52, s22, 0x40000
	v_lshl_add_u64 v[206:207], s[22:23], 0, v[134:135]
	s_addc_u32 s53, s23, 0
	s_add_i32 s39, s45, s26
	global_load_lds_dwordx4 v[206:207], off
	v_lshl_add_u64 v[248:249], s[52:53], 0, v[130:131]
	s_mov_b32 m0, s39
	v_lshl_add_u64 v[250:251], s[24:25], 0, v[132:133]
	global_load_lds_dwordx4 v[248:249], off
	v_lshl_add_u64 v[248:249], s[52:53], 0, v[134:135]
	s_add_i32 m0, s39, 0x2000
	s_nop 0
	global_load_lds_dwordx4 v[248:249], off
	v_lshl_add_u64 v[248:249], s[24:25], 0, v[128:129]
	s_mov_b32 m0, s19
	s_nop 0
	global_load_lds_dwordx4 v[248:249], off
	s_mov_b32 m0, s27
	s_nop 0
	global_load_lds_dwordx4 v[250:251], off
	s_waitcnt vmcnt(8)
	s_waitcnt lgkmcnt(0)
	s_barrier
; #define PG8_STAGE(bufoff, gbase, voff) do { _Pragma("unroll") for (int _i = 0; _i < 2; ++_i) \
;         __builtin_amdgcn_global_load_lds((const unsigned*)((const char*)(gbase) + (voff)[_i]), (PG8_LAS unsigned*)(lds + (bufoff) + ldsw + _i * 8192), 16, 0, 0); } while (0)
; #define PG8_LDA(dst, b, h) do { _Pragma("unroll") for (int m = 0; m < 4; ++m) _Pragma("unroll") for (int k = 0; k < 2; ++k) dst[m][k] = *(const PG8_LAS bf16x8*)(lds + PG8_SA(b, h) + aoff + m * 2048 + k * 1024); } while (0)
; #define PG8_LDB(dst, b, h) do { _Pragma("unroll") for (int n = 0; n < 2; ++n) _Pragma("unroll") for (int k = 0; k < 2; ++k) dst[n][k] = *(const PG8_LAS bf16x8*)(lds + PG8_SB(b, h) + boff + n * 2048 + k * 1024); } while (0)
; #define PG8_MMA(ai, bj, At, Bt) do { __builtin_amdgcn_s_setprio(1); _Pragma("unroll") for (int m = 0; m < 4; ++m) _Pragma("unroll") for (int n = 0; n < 2; ++n) _Pragma("unroll") for (int k = 0; k < 2; ++k) \
;         acc[ai][bj][m][n] = __builtin_amdgcn_mfma_f32_16x16x32_bf16(Bt[n][k], At[m][k], acc[ai][bj][m][n], 0, 0, 0); __builtin_amdgcn_s_setprio(0); } while (0)
; #define PG8_WAIT_V(n) asm volatile("s_waitcnt vmcnt(" #n ")" ::: "memory")
; #define PG8_WAIT_L(n) asm volatile("s_waitcnt lgkmcnt(" #n ")" ::: "memory")
; #define PG8_BAR __builtin_amdgcn_s_barrier()
; #define PG8_SCHED __builtin_amdgcn_sched_barrier(0)
; template <class Epi, class Sched, bool ALIGN_EPI = false, bool SP2 = false>
; __device__ __forceinline__ void gemm_phase(PG8_LAS unsigned char* lds, const Gemm g, const Sched& S, const Epi& E) {
;     ...
;             PG8_WAIT_V(8); PG8_WAIT_L(0); PG8_BAR; PG8_MMA(1, 0, At, B0); PG8_MMA(1, 1, At, B1); PG8_BAR; PG8_SCHED;
;             PG8_LDB(B0, 1, 0); PG8_LDB(B1, 1, 1); PG8_SCHED; PG8_LDA(At, 1, 0); PG8_STAGE(PG8_SA(0, 1), a2 + hstep, voffA);
;             PG8_WAIT_V(8); PG8_WAIT_L(0); PG8_BAR; PG8_MMA(0, 0, At, B0); PG8_MMA(0, 1, At, B1); PG8_BAR; PG8_SCHED;
	s_setprio 1
	s_waitcnt lgkmcnt(0)
	v_mfma_f32_16x16x32_bf16 v[60:63], v[140:143], v[190:193], v[60:63]
	v_mfma_f32_16x16x32_bf16 v[56:59], v[156:159], v[190:193], v[56:59]
	v_mfma_f32_16x16x32_bf16 v[44:47], v[140:143], v[198:201], v[44:47]
	v_mfma_f32_16x16x32_bf16 v[40:43], v[156:159], v[198:201], v[40:43]
	v_mfma_f32_16x16x32_bf16 v[28:31], v[140:143], v[228:231], v[28:31]
	v_mfma_f32_16x16x32_bf16 v[24:27], v[156:159], v[228:231], v[24:27]
	v_mfma_f32_16x16x32_bf16 v[12:15], v[140:143], v[240:243], v[12:15]
	v_mfma_f32_16x16x32_bf16 v[8:11], v[156:159], v[240:243], v[8:11]
	v_mfma_f32_16x16x32_bf16 v[60:63], v[144:147], v[194:197], v[60:63]
	v_mfma_f32_16x16x32_bf16 v[56:59], v[160:163], v[194:197], v[56:59]
	v_mfma_f32_16x16x32_bf16 v[44:47], v[144:147], v[202:205], v[44:47]
	v_mfma_f32_16x16x32_bf16 v[40:43], v[160:163], v[202:205], v[40:43]
	v_mfma_f32_16x16x32_bf16 v[28:31], v[144:147], v[236:239], v[28:31]
	v_mfma_f32_16x16x32_bf16 v[24:27], v[160:163], v[236:239], v[24:27]
	v_mfma_f32_16x16x32_bf16 v[12:15], v[144:147], v[244:247], v[12:15]
	v_mfma_f32_16x16x32_bf16 v[8:11], v[160:163], v[244:247], v[8:11]
	s_setprio 0
	s_setprio 1
	v_mfma_f32_16x16x32_bf16 v[52:55], v[164:167], v[190:193], v[52:55]
	v_mfma_f32_16x16x32_bf16 v[48:51], v[182:185], v[190:193], v[48:51]
	v_mfma_f32_16x16x32_bf16 v[36:39], v[164:167], v[198:201], v[36:39]
	v_mfma_f32_16x16x32_bf16 v[32:35], v[182:185], v[198:201], v[32:35]
	v_mfma_f32_16x16x32_bf16 v[20:23], v[164:167], v[228:231], v[20:23]
	v_mfma_f32_16x16x32_bf16 v[16:19], v[182:185], v[228:231], v[16:19]
	v_mfma_f32_16x16x32_bf16 v[4:7], v[164:167], v[240:243], v[4:7]
	v_mfma_f32_16x16x32_bf16 v[0:3], v[182:185], v[240:243], v[0:3]
	s_setprio 2
	s_barrier
	v_mfma_f32_16x16x32_bf16 v[52:55], v[168:171], v[194:197], v[52:55]
	v_mfma_f32_16x16x32_bf16 v[48:51], v[186:189], v[194:197], v[48:51]
	v_mfma_f32_16x16x32_bf16 v[36:39], v[168:171], v[202:205], v[36:39]
	v_mfma_f32_16x16x32_bf16 v[32:35], v[186:189], v[202:205], v[32:35]
	v_mfma_f32_16x16x32_bf16 v[20:23], v[168:171], v[236:239], v[20:23]
	v_mfma_f32_16x16x32_bf16 v[16:19], v[186:189], v[236:239], v[16:19]
	v_mfma_f32_16x16x32_bf16 v[4:7], v[168:171], v[244:247], v[4:7]
	v_mfma_f32_16x16x32_bf16 v[0:3], v[186:189], v[244:247], v[0:3]
	s_setprio 0
	s_add_i32 s39, 0, 0x18000
	v_add_u32_e32 v155, s39, v151
	s_add_i32 s45, 0, 0x1c000
	ds_read_b128 v[140:143], v155
	ds_read_b128 v[144:147], v155 offset:1024
	ds_read_b128 v[156:159], v155 offset:2048
	ds_read_b128 v[160:163], v155 offset:3072
	v_add_u32_e32 v155, s45, v151
	ds_read_b128 v[164:167], v155
	ds_read_b128 v[168:171], v155 offset:1024
	ds_read_b128 v[182:185], v155 offset:2048
	ds_read_b128 v[186:189], v155 offset:3072
	s_add_u32 s24, s24, 0x40000
	s_addc_u32 s25, s25, 0
	s_mov_b32 m0, s28
	v_lshl_add_u64 v[210:211], s[24:25], 0, v[128:129]
	ds_read_b128 v[190:193], v154 offset:32768
	ds_read_b128 v[194:197], v154 offset:33792
	ds_read_b128 v[198:201], v154 offset:34816
	ds_read_b128 v[202:205], v154 offset:35840
	ds_read_b128 v[228:231], v154 offset:36864
	ds_read_b128 v[236:239], v154 offset:37888
	ds_read_b128 v[240:243], v154 offset:38912
	ds_read_b128 v[244:247], v154 offset:39936
	global_load_lds_dwordx4 v[210:211], off
	v_lshl_add_u64 v[210:211], s[24:25], 0, v[132:133]
	s_mov_b32 m0, s29
	s_nop 0
	global_load_lds_dwordx4 v[210:211], off
	s_waitcnt vmcnt(8)
	s_waitcnt lgkmcnt(0)
	s_barrier
	s_setprio 1
	s_waitcnt lgkmcnt(0)
	v_mfma_f32_16x16x32_bf16 v[124:127], v[140:143], v[190:193], v[124:127]
	v_mfma_f32_16x16x32_bf16 v[120:123], v[156:159], v[190:193], v[120:123]
	v_mfma_f32_16x16x32_bf16 v[108:111], v[140:143], v[198:201], v[108:111]
	v_mfma_f32_16x16x32_bf16 v[104:107], v[156:159], v[198:201], v[104:107]
	v_mfma_f32_16x16x32_bf16 v[92:95], v[140:143], v[228:231], v[92:95]
	v_mfma_f32_16x16x32_bf16 v[88:91], v[156:159], v[228:231], v[88:91]
	v_mfma_f32_16x16x32_bf16 v[76:79], v[140:143], v[240:243], v[76:79]
	v_mfma_f32_16x16x32_bf16 v[72:75], v[156:159], v[240:243], v[72:75]
	v_mfma_f32_16x16x32_bf16 v[124:127], v[144:147], v[194:197], v[124:127]
	v_mfma_f32_16x16x32_bf16 v[120:123], v[160:163], v[194:197], v[120:123]
	v_mfma_f32_16x16x32_bf16 v[108:111], v[144:147], v[202:205], v[108:111]
	v_mfma_f32_16x16x32_bf16 v[104:107], v[160:163], v[202:205], v[104:107]
	v_mfma_f32_16x16x32_bf16 v[92:95], v[144:147], v[236:239], v[92:95]
	v_mfma_f32_16x16x32_bf16 v[88:91], v[160:163], v[236:239], v[88:91]
	v_mfma_f32_16x16x32_bf16 v[76:79], v[144:147], v[244:247], v[76:79]
	v_mfma_f32_16x16x32_bf16 v[72:75], v[160:163], v[244:247], v[72:75]
	s_setprio 0
	s_setprio 1
	v_mfma_f32_16x16x32_bf16 v[116:119], v[164:167], v[190:193], v[116:119]
	v_mfma_f32_16x16x32_bf16 v[112:115], v[182:185], v[190:193], v[112:115]
	v_mfma_f32_16x16x32_bf16 v[100:103], v[164:167], v[198:201], v[100:103]
	v_mfma_f32_16x16x32_bf16 v[96:99], v[182:185], v[198:201], v[96:99]
	v_mfma_f32_16x16x32_bf16 v[84:87], v[164:167], v[228:231], v[84:87]
	v_mfma_f32_16x16x32_bf16 v[80:83], v[182:185], v[228:231], v[80:83]
	v_mfma_f32_16x16x32_bf16 v[68:71], v[164:167], v[240:243], v[68:71]
	v_mfma_f32_16x16x32_bf16 v[64:67], v[182:185], v[240:243], v[64:67]
	s_setprio 2
	s_barrier
; #define PG8_STAGE(bufoff, gbase, voff) do { _Pragma("unroll") for (int _i = 0; _i < 2; ++_i) \
;         __builtin_amdgcn_global_load_lds((const unsigned*)((const char*)(gbase) + (voff)[_i]), (PG8_LAS unsigned*)(lds + (bufoff) + ldsw + _i * 8192), 16, 0, 0); } while (0)
; #define PG8_LDA(dst, b, h) do { _Pragma("unroll") for (int m = 0; m < 4; ++m) _Pragma("unroll") for (int k = 0; k < 2; ++k) dst[m][k] = *(const PG8_LAS bf16x8*)(lds + PG8_SA(b, h) + aoff + m * 2048 + k * 1024); } while (0)
; #define PG8_MMA(ai, bj, At, Bt) do { __builtin_amdgcn_s_setprio(1); _Pragma("unroll") for (int m = 0; m < 4; ++m) _Pragma("unroll") for (int n = 0; n < 2; ++n) _Pragma("unroll") for (int k = 0; k < 2; ++k) \
;         acc[ai][bj][m][n] = __builtin_amdgcn_mfma_f32_16x16x32_bf16(Bt[n][k], At[m][k], acc[ai][bj][m][n], 0, 0, 0); __builtin_amdgcn_s_setprio(0); } while (0)
; #define PG8_WAIT_V(n) asm volatile("s_waitcnt vmcnt(" #n ")" ::: "memory")
; #define PG8_WAIT_L(n) asm volatile("s_waitcnt lgkmcnt(" #n ")" ::: "memory")
; #define PG8_BAR __builtin_amdgcn_s_barrier()
; #define PG8_SCHED __builtin_amdgcn_sched_barrier(0)
; template <class Epi, class Sched, bool ALIGN_EPI = false, bool SP2 = false>
; __device__ __forceinline__ void gemm_phase(PG8_LAS unsigned char* lds, const Gemm g, const Sched& S, const Epi& E) {
;     ...
;             PG8_WAIT_V(8); PG8_WAIT_L(0); PG8_BAR; PG8_MMA(0, 0, At, B0); PG8_MMA(0, 1, At, B1); PG8_BAR; PG8_SCHED;
;             PG8_LDA(At, 1, 1); PG8_STAGE(PG8_SB(1, 0), b3, voffB); PG8_STAGE(PG8_SB(1, 1), b3 + hstep, voffB); PG8_STAGE(PG8_SA(1, 0), a3, voffA);
;             PG8_WAIT_V(8); PG8_WAIT_L(0); PG8_BAR; PG8_MMA(1, 0, At, B0); PG8_MMA(1, 1, At, B1); PG8_BAR; PG8_SCHED;
;     ...
;         }
;         if constexpr (ALIGN_EPI) { if (wr == 0) PG8_BAR; }
	v_mfma_f32_16x16x32_bf16 v[116:119], v[168:171], v[194:197], v[116:119]
	v_mfma_f32_16x16x32_bf16 v[112:115], v[186:189], v[194:197], v[112:115]
	v_mfma_f32_16x16x32_bf16 v[100:103], v[168:171], v[202:205], v[100:103]
	v_mfma_f32_16x16x32_bf16 v[96:99], v[186:189], v[202:205], v[96:99]
	v_mfma_f32_16x16x32_bf16 v[84:87], v[168:171], v[236:239], v[84:87]
	v_mfma_f32_16x16x32_bf16 v[80:83], v[186:189], v[236:239], v[80:83]
	v_mfma_f32_16x16x32_bf16 v[68:71], v[168:171], v[244:247], v[68:71]
	v_mfma_f32_16x16x32_bf16 v[64:67], v[186:189], v[244:247], v[64:67]
	s_setprio 0
	s_add_i32 s24, s39, s26
	v_lshl_add_u64 v[148:149], v[148:149], 0, s[88:89]
	s_mov_b32 m0, s24
	ds_read_b128 v[190:193], v154 offset:49152
	ds_read_b128 v[194:197], v154 offset:50176
	ds_read_b128 v[198:201], v154 offset:51200
	ds_read_b128 v[202:205], v154 offset:52224
	ds_read_b128 v[228:231], v154 offset:53248
	ds_read_b128 v[236:239], v154 offset:54272
	ds_read_b128 v[240:243], v154 offset:55296
	ds_read_b128 v[244:247], v154 offset:56320
	global_load_lds_dwordx4 v[148:149], off
	s_add_i32 m0, s24, 0x2000
	s_add_u32 s22, s22, 0x40080
	v_lshl_add_u64 v[148:149], v[206:207], 0, s[88:89]
	s_addc_u32 s23, s23, 0
	s_add_i32 s24, s45, s26
	global_load_lds_dwordx4 v[148:149], off
	v_lshl_add_u64 v[148:149], s[22:23], 0, v[130:131]
	s_mov_b32 m0, s24
	s_nop 0
	global_load_lds_dwordx4 v[148:149], off
	v_lshl_add_u64 v[148:149], s[22:23], 0, v[134:135]
	s_add_i32 m0, s24, 0x2000
	s_nop 0
	global_load_lds_dwordx4 v[148:149], off
	v_lshl_add_u64 v[148:149], v[248:249], 0, s[88:89]
	s_mov_b32 m0, s30
	s_nop 0
	global_load_lds_dwordx4 v[148:149], off
	v_lshl_add_u64 v[148:149], v[250:251], 0, s[88:89]
	s_mov_b32 m0, s31
	s_nop 0
	global_load_lds_dwordx4 v[148:149], off
	s_waitcnt vmcnt(8)
	s_waitcnt lgkmcnt(0)
	s_barrier
	s_setprio 1
	s_waitcnt lgkmcnt(0)
	v_mfma_f32_16x16x32_bf16 v[60:63], v[140:143], v[190:193], v[60:63]
	v_mfma_f32_16x16x32_bf16 v[56:59], v[156:159], v[190:193], v[56:59]
	v_mfma_f32_16x16x32_bf16 v[44:47], v[140:143], v[198:201], v[44:47]
	v_mfma_f32_16x16x32_bf16 v[40:43], v[156:159], v[198:201], v[40:43]
	v_mfma_f32_16x16x32_bf16 v[28:31], v[140:143], v[228:231], v[28:31]
	v_mfma_f32_16x16x32_bf16 v[24:27], v[156:159], v[228:231], v[24:27]
	v_mfma_f32_16x16x32_bf16 v[12:15], v[140:143], v[240:243], v[12:15]
	v_mfma_f32_16x16x32_bf16 v[8:11], v[156:159], v[240:243], v[8:11]
	v_mfma_f32_16x16x32_bf16 v[60:63], v[144:147], v[194:197], v[60:63]
	v_mfma_f32_16x16x32_bf16 v[56:59], v[160:163], v[194:197], v[56:59]
	v_mfma_f32_16x16x32_bf16 v[44:47], v[144:147], v[202:205], v[44:47]
	v_mfma_f32_16x16x32_bf16 v[40:43], v[160:163], v[202:205], v[40:43]
	v_mfma_f32_16x16x32_bf16 v[28:31], v[144:147], v[236:239], v[28:31]
	v_mfma_f32_16x16x32_bf16 v[24:27], v[160:163], v[236:239], v[24:27]
	v_mfma_f32_16x16x32_bf16 v[12:15], v[144:147], v[244:247], v[12:15]
	v_mfma_f32_16x16x32_bf16 v[8:11], v[160:163], v[244:247], v[8:11]
	s_setprio 0
	s_setprio 1
	v_mfma_f32_16x16x32_bf16 v[52:55], v[164:167], v[190:193], v[52:55]
	v_mfma_f32_16x16x32_bf16 v[48:51], v[182:185], v[190:193], v[48:51]
	v_mfma_f32_16x16x32_bf16 v[36:39], v[164:167], v[198:201], v[36:39]
	v_mfma_f32_16x16x32_bf16 v[32:35], v[182:185], v[198:201], v[32:35]
	v_mfma_f32_16x16x32_bf16 v[20:23], v[164:167], v[228:231], v[20:23]
	v_mfma_f32_16x16x32_bf16 v[16:19], v[182:185], v[228:231], v[16:19]
	v_mfma_f32_16x16x32_bf16 v[4:7], v[164:167], v[240:243], v[4:7]
	v_mfma_f32_16x16x32_bf16 v[0:3], v[182:185], v[240:243], v[0:3]
	s_setprio 2
	s_barrier
	v_mfma_f32_16x16x32_bf16 v[52:55], v[168:171], v[194:197], v[52:55]
	v_mfma_f32_16x16x32_bf16 v[48:51], v[186:189], v[194:197], v[48:51]
	v_mfma_f32_16x16x32_bf16 v[36:39], v[168:171], v[202:205], v[36:39]
	v_mfma_f32_16x16x32_bf16 v[32:35], v[186:189], v[202:205], v[32:35]
	v_mfma_f32_16x16x32_bf16 v[20:23], v[168:171], v[236:239], v[20:23]
	v_mfma_f32_16x16x32_bf16 v[16:19], v[186:189], v[236:239], v[16:19]
	v_mfma_f32_16x16x32_bf16 v[4:7], v[168:171], v[244:247], v[4:7]
	v_mfma_f32_16x16x32_bf16 v[0:3], v[186:189], v[244:247], v[0:3]
	s_setprio 0
	s_add_i32 s38, s38, 2
	s_add_u32 s20, s20, 0x100
	s_addc_u32 s21, s21, 0
	s_add_u32 s36, s36, 0x100
	s_addc_u32 s37, s37, 0
	s_cmp_gt_u32 s38, 13
	s_cbranch_scc0 .LBB0_274
	s_and_b64 vcc, exec, s[8:9]
	s_cbranch_vccz .LBB0_295
	s_barrier
	v_lshl_add_u32 v155, s4, 8, v150
	s_cmp_gt_i32 s18, 7
	s_mov_b64 s[4:5], -1
	s_cbranch_scc1 .LBB0_296

; #define PG8_STAGE(bufoff, gbase, voff) do { _Pragma("unroll") for (int _i = 0; _i < 2; ++_i) \
;         __builtin_amdgcn_global_load_lds((const unsigned*)((const char*)(gbase) + (voff)[_i]), (PG8_LAS unsigned*)(lds + (bufoff) + ldsw + _i * 8192), 16, 0, 0); } while (0)
; #define PG8_LDA(dst, b, h) do { _Pragma("unroll") for (int m = 0; m < 4; ++m) _Pragma("unroll") for (int k = 0; k < 2; ++k) dst[m][k] = *(const PG8_LAS bf16x8*)(lds + PG8_SA(b, h) + aoff + m * 2048 + k * 1024); } while (0)
; #define PG8_LDB(dst, b, h) do { _Pragma("unroll") for (int n = 0; n < 2; ++n) _Pragma("unroll") for (int k = 0; k < 2; ++k) dst[n][k] = *(const PG8_LAS bf16x8*)(lds + PG8_SB(b, h) + boff + n * 2048 + k * 1024); } while (0)
; #define PG8_MMA(ai, bj, At, Bt) do { __builtin_amdgcn_s_setprio(1); _Pragma("unroll") for (int m = 0; m < 4; ++m) _Pragma("unroll") for (int n = 0; n < 2; ++n) _Pragma("unroll") for (int k = 0; k < 2; ++k) \
;         acc[ai][bj][m][n] = __builtin_amdgcn_mfma_f32_16x16x32_bf16(Bt[n][k], At[m][k], acc[ai][bj][m][n], 0, 0, 0); __builtin_amdgcn_s_setprio(0); } while (0)
; #define PG8_WAIT_V(n) asm volatile("s_waitcnt vmcnt(" #n ")" ::: "memory")
; #define PG8_WAIT_L(n) asm volatile("s_waitcnt lgkmcnt(" #n ")" ::: "memory")
; #define PG8_BAR __builtin_amdgcn_s_barrier()
; #define PG8_SCHED __builtin_amdgcn_sched_barrier(0)
; template <class Epi, class Sched, bool ALIGN_EPI = false, bool SP2 = false>
; __device__ __forceinline__ void gemm_phase(PG8_LAS unsigned char* lds, const Gemm g, const Sched& S, const Epi& E) {
;     ...
;             PG8_LDB(B0, 0, 0); PG8_LDB(B1, 0, 1); PG8_SCHED; PG8_LDA(At, 0, 0); PG8_STAGE(PG8_SA(1, 1), a1 + hstep, voffA);
;             PG8_WAIT_V(8); PG8_WAIT_L(0); PG8_BAR; PG8_MMA(0, 0, At, B0); PG8_MMA(0, 1, At, B1); PG8_BAR; PG8_SCHED;
;             PG8_LDA(At, 0, 1); PG8_STAGE(PG8_SB(0, 0), b2, voffB); PG8_STAGE(PG8_SB(0, 1), b2 + hstep, voffB); PG8_STAGE(PG8_SA(0, 0), a2, voffA);
;             PG8_WAIT_V(8); PG8_WAIT_L(0); PG8_BAR; PG8_MMA(1, 0, At, B0); PG8_MMA(1, 1, At, B1); PG8_BAR; PG8_SCHED;
.LBB0_613:
	s_add_u32 s36, s34, 0xfffc0080
	s_addc_u32 s37, s35, -1
	s_add_i32 s68, 0, 0x10000
	s_cmp_eq_u32 s67, 12
	s_cselect_b32 s39, s27, s37
	s_cselect_b32 s38, s63, s36
	s_cselect_b32 s37, s25, s66
	s_cselect_b32 s36, s64, s65
	s_add_i32 s70, 0, 0x14000
	v_add_u32_e32 v84, s68, v228
	v_add_u32_e32 v156, s70, v228
	ds_read_b128 v[68:71], v84
	ds_read_b128 v[72:75], v84 offset:1024
	ds_read_b128 v[80:83], v84 offset:2048
	ds_read_b128 v[84:87], v84 offset:3072
	ds_read_b128 v[144:147], v156
	ds_read_b128 v[148:151], v156 offset:1024
	ds_read_b128 v[152:155], v156 offset:2048
	ds_read_b128 v[156:159], v156 offset:3072
	v_lshl_add_u64 v[210:211], s[34:35], 0, v[188:189]
	s_add_i32 m0, s52, 0xc000
	ds_read_b128 v[160:163], v230
	ds_read_b128 v[164:167], v230 offset:1024
	ds_read_b128 v[168:171], v230 offset:2048
	ds_read_b128 v[192:195], v230 offset:3072
	ds_read_b128 v[196:199], v230 offset:4096
	ds_read_b128 v[200:203], v230 offset:5120
	ds_read_b128 v[204:207], v230 offset:6144
	ds_read_b128 v[236:239], v230 offset:7168
	global_load_lds_dwordx4 v[210:211], off
	v_lshl_add_u64 v[210:211], s[34:35], 0, v[190:191]
	s_add_i32 m0, s52, 0xe000
	s_nop 0
	global_load_lds_dwordx4 v[210:211], off
	s_waitcnt vmcnt(8)
	s_waitcnt lgkmcnt(0)
	s_barrier
	s_setprio 1
	s_waitcnt lgkmcnt(0)
	v_mfma_f32_16x16x32_bf16 v[140:143], v[68:71], v[160:163], v[140:143]
	v_mfma_f32_16x16x32_bf16 v[136:139], v[80:83], v[160:163], v[136:139]
	v_mfma_f32_16x16x32_bf16 v[124:127], v[68:71], v[168:171], v[124:127]
	v_mfma_f32_16x16x32_bf16 v[120:123], v[80:83], v[168:171], v[120:123]
	v_mfma_f32_16x16x32_bf16 v[108:111], v[68:71], v[196:199], v[108:111]
	v_mfma_f32_16x16x32_bf16 v[104:107], v[80:83], v[196:199], v[104:107]
	v_mfma_f32_16x16x32_bf16 v[92:95], v[68:71], v[204:207], v[92:95]
	v_mfma_f32_16x16x32_bf16 v[88:91], v[80:83], v[204:207], v[88:91]
	v_mfma_f32_16x16x32_bf16 v[140:143], v[72:75], v[164:167], v[140:143]
	v_mfma_f32_16x16x32_bf16 v[136:139], v[84:87], v[164:167], v[136:139]
	v_mfma_f32_16x16x32_bf16 v[124:127], v[72:75], v[192:195], v[124:127]
	v_mfma_f32_16x16x32_bf16 v[120:123], v[84:87], v[192:195], v[120:123]
	v_mfma_f32_16x16x32_bf16 v[108:111], v[72:75], v[200:203], v[108:111]
	v_mfma_f32_16x16x32_bf16 v[104:107], v[84:87], v[200:203], v[104:107]
	v_mfma_f32_16x16x32_bf16 v[92:95], v[72:75], v[236:239], v[92:95]
	v_mfma_f32_16x16x32_bf16 v[88:91], v[84:87], v[236:239], v[88:91]
	s_setprio 0
	s_setprio 1
	v_mfma_f32_16x16x32_bf16 v[132:135], v[144:147], v[160:163], v[132:135]
	v_mfma_f32_16x16x32_bf16 v[128:131], v[152:155], v[160:163], v[128:131]
	v_mfma_f32_16x16x32_bf16 v[116:119], v[144:147], v[168:171], v[116:119]
	v_mfma_f32_16x16x32_bf16 v[112:115], v[152:155], v[168:171], v[112:115]
	v_mfma_f32_16x16x32_bf16 v[100:103], v[144:147], v[196:199], v[100:103]
	v_mfma_f32_16x16x32_bf16 v[96:99], v[152:155], v[196:199], v[96:99]
	v_mfma_f32_16x16x32_bf16 v[76:79], v[144:147], v[204:207], v[76:79]
	v_mfma_f32_16x16x32_bf16 v[64:67], v[152:155], v[204:207], v[64:67]
	s_setprio 2
	s_barrier
	v_mfma_f32_16x16x32_bf16 v[132:135], v[148:151], v[164:167], v[132:135]
	v_mfma_f32_16x16x32_bf16 v[128:131], v[156:159], v[164:167], v[128:131]
	v_mfma_f32_16x16x32_bf16 v[116:119], v[148:151], v[192:195], v[116:119]
	v_mfma_f32_16x16x32_bf16 v[112:115], v[156:159], v[192:195], v[112:115]
	v_mfma_f32_16x16x32_bf16 v[100:103], v[148:151], v[200:203], v[100:103]
	v_mfma_f32_16x16x32_bf16 v[96:99], v[156:159], v[200:203], v[96:99]
	v_mfma_f32_16x16x32_bf16 v[76:79], v[148:151], v[236:239], v[76:79]
	v_mfma_f32_16x16x32_bf16 v[64:67], v[156:159], v[236:239], v[64:67]
	s_setprio 0
	s_add_i32 s68, s68, s45
	v_lshl_add_u64 v[210:211], s[36:37], 0, v[172:173]
	s_mov_b32 m0, s68
	ds_read_b128 v[160:163], v230 offset:16384
	ds_read_b128 v[164:167], v230 offset:17408
	ds_read_b128 v[168:171], v230 offset:18432
	ds_read_b128 v[192:195], v230 offset:19456
	ds_read_b128 v[196:199], v230 offset:20480
	ds_read_b128 v[200:203], v230 offset:21504
	ds_read_b128 v[204:207], v230 offset:22528
	ds_read_b128 v[236:239], v230 offset:23552
	global_load_lds_dwordx4 v[210:211], off
	s_add_i32 m0, s68, 0x2000
	s_add_u32 s68, s36, 0x40000
	v_lshl_add_u64 v[240:241], s[36:37], 0, v[182:183]
	s_addc_u32 s69, s37, 0
	s_add_i32 s70, s70, s45
	global_load_lds_dwordx4 v[240:241], off
	v_lshl_add_u64 v[242:243], s[68:69], 0, v[172:173]
	s_mov_b32 m0, s70
	v_lshl_add_u64 v[244:245], s[38:39], 0, v[184:185]
	global_load_lds_dwordx4 v[242:243], off
	v_lshl_add_u64 v[242:243], s[68:69], 0, v[182:183]
	s_add_i32 m0, s70, 0x2000
	s_nop 0
	global_load_lds_dwordx4 v[242:243], off
	v_lshl_add_u64 v[242:243], s[38:39], 0, v[186:187]
	s_mov_b32 m0, s52
	s_nop 0
	global_load_lds_dwordx4 v[242:243], off
	s_mov_b32 m0, s53
	s_nop 0
	global_load_lds_dwordx4 v[244:245], off
	s_waitcnt vmcnt(8)
	s_waitcnt lgkmcnt(0)
	s_barrier
; #define PG8_STAGE(bufoff, gbase, voff) do { _Pragma("unroll") for (int _i = 0; _i < 2; ++_i) \
;         __builtin_amdgcn_global_load_lds((const unsigned*)((const char*)(gbase) + (voff)[_i]), (PG8_LAS unsigned*)(lds + (bufoff) + ldsw + _i * 8192), 16, 0, 0); } while (0)
; #define PG8_LDA(dst, b, h) do { _Pragma("unroll") for (int m = 0; m < 4; ++m) _Pragma("unroll") for (int k = 0; k < 2; ++k) dst[m][k] = *(const PG8_LAS bf16x8*)(lds + PG8_SA(b, h) + aoff + m * 2048 + k * 1024); } while (0)
; #define PG8_LDB(dst, b, h) do { _Pragma("unroll") for (int n = 0; n < 2; ++n) _Pragma("unroll") for (int k = 0; k < 2; ++k) dst[n][k] = *(const PG8_LAS bf16x8*)(lds + PG8_SB(b, h) + boff + n * 2048 + k * 1024); } while (0)
; #define PG8_MMA(ai, bj, At, Bt) do { __builtin_amdgcn_s_setprio(1); _Pragma("unroll") for (int m = 0; m < 4; ++m) _Pragma("unroll") for (int n = 0; n < 2; ++n) _Pragma("unroll") for (int k = 0; k < 2; ++k) \
;         acc[ai][bj][m][n] = __builtin_amdgcn_mfma_f32_16x16x32_bf16(Bt[n][k], At[m][k], acc[ai][bj][m][n], 0, 0, 0); __builtin_amdgcn_s_setprio(0); } while (0)
; #define PG8_WAIT_V(n) asm volatile("s_waitcnt vmcnt(" #n ")" ::: "memory")
; #define PG8_WAIT_L(n) asm volatile("s_waitcnt lgkmcnt(" #n ")" ::: "memory")
; #define PG8_BAR __builtin_amdgcn_s_barrier()
; #define PG8_SCHED __builtin_amdgcn_sched_barrier(0)
; template <class Epi, class Sched, bool ALIGN_EPI = false, bool SP2 = false>
; __device__ __forceinline__ void gemm_phase(PG8_LAS unsigned char* lds, const Gemm g, const Sched& S, const Epi& E) {
;     ...
;             PG8_WAIT_V(8); PG8_WAIT_L(0); PG8_BAR; PG8_MMA(1, 0, At, B0); PG8_MMA(1, 1, At, B1); PG8_BAR; PG8_SCHED;
;             PG8_LDB(B0, 1, 0); PG8_LDB(B1, 1, 1); PG8_SCHED; PG8_LDA(At, 1, 0); PG8_STAGE(PG8_SA(0, 1), a2 + hstep, voffA);
;             PG8_WAIT_V(8); PG8_WAIT_L(0); PG8_BAR; PG8_MMA(0, 0, At, B0); PG8_MMA(0, 1, At, B1); PG8_BAR; PG8_SCHED;
	s_setprio 1
	s_waitcnt lgkmcnt(0)
	v_mfma_f32_16x16x32_bf16 v[60:63], v[68:71], v[160:163], v[60:63]
	v_mfma_f32_16x16x32_bf16 v[56:59], v[80:83], v[160:163], v[56:59]
	v_mfma_f32_16x16x32_bf16 v[44:47], v[68:71], v[168:171], v[44:47]
	v_mfma_f32_16x16x32_bf16 v[40:43], v[80:83], v[168:171], v[40:43]
	v_mfma_f32_16x16x32_bf16 v[28:31], v[68:71], v[196:199], v[28:31]
	v_mfma_f32_16x16x32_bf16 v[24:27], v[80:83], v[196:199], v[24:27]
	v_mfma_f32_16x16x32_bf16 v[12:15], v[68:71], v[204:207], v[12:15]
	v_mfma_f32_16x16x32_bf16 v[8:11], v[80:83], v[204:207], v[8:11]
	v_mfma_f32_16x16x32_bf16 v[60:63], v[72:75], v[164:167], v[60:63]
	v_mfma_f32_16x16x32_bf16 v[56:59], v[84:87], v[164:167], v[56:59]
	v_mfma_f32_16x16x32_bf16 v[44:47], v[72:75], v[192:195], v[44:47]
	v_mfma_f32_16x16x32_bf16 v[40:43], v[84:87], v[192:195], v[40:43]
	v_mfma_f32_16x16x32_bf16 v[28:31], v[72:75], v[200:203], v[28:31]
	v_mfma_f32_16x16x32_bf16 v[24:27], v[84:87], v[200:203], v[24:27]
	v_mfma_f32_16x16x32_bf16 v[12:15], v[72:75], v[236:239], v[12:15]
	v_mfma_f32_16x16x32_bf16 v[8:11], v[84:87], v[236:239], v[8:11]
	s_setprio 0
	s_setprio 1
	v_mfma_f32_16x16x32_bf16 v[52:55], v[144:147], v[160:163], v[52:55]
	v_mfma_f32_16x16x32_bf16 v[48:51], v[152:155], v[160:163], v[48:51]
	v_mfma_f32_16x16x32_bf16 v[36:39], v[144:147], v[168:171], v[36:39]
	v_mfma_f32_16x16x32_bf16 v[32:35], v[152:155], v[168:171], v[32:35]
	v_mfma_f32_16x16x32_bf16 v[20:23], v[144:147], v[196:199], v[20:23]
	v_mfma_f32_16x16x32_bf16 v[16:19], v[152:155], v[196:199], v[16:19]
	v_mfma_f32_16x16x32_bf16 v[4:7], v[144:147], v[204:207], v[4:7]
	v_mfma_f32_16x16x32_bf16 v[0:3], v[152:155], v[204:207], v[0:3]
	s_setprio 2
	s_barrier
	v_mfma_f32_16x16x32_bf16 v[52:55], v[148:151], v[164:167], v[52:55]
	v_mfma_f32_16x16x32_bf16 v[48:51], v[156:159], v[164:167], v[48:51]
	v_mfma_f32_16x16x32_bf16 v[36:39], v[148:151], v[192:195], v[36:39]
	v_mfma_f32_16x16x32_bf16 v[32:35], v[156:159], v[192:195], v[32:35]
	v_mfma_f32_16x16x32_bf16 v[20:23], v[148:151], v[200:203], v[20:23]
	v_mfma_f32_16x16x32_bf16 v[16:19], v[156:159], v[200:203], v[16:19]
	v_mfma_f32_16x16x32_bf16 v[4:7], v[148:151], v[236:239], v[4:7]
	v_mfma_f32_16x16x32_bf16 v[0:3], v[156:159], v[236:239], v[0:3]
	s_setprio 0
	s_add_i32 s68, 0, 0x18000
	s_add_i32 s69, 0, 0x1c000
	v_add_u32_e32 v84, s68, v228
	v_add_u32_e32 v156, s69, v228
	ds_read_b128 v[68:71], v84
	ds_read_b128 v[72:75], v84 offset:1024
	ds_read_b128 v[80:83], v84 offset:2048
	ds_read_b128 v[84:87], v84 offset:3072
	ds_read_b128 v[144:147], v156
	ds_read_b128 v[148:151], v156 offset:1024
	ds_read_b128 v[152:155], v156 offset:2048
	ds_read_b128 v[156:159], v156 offset:3072
	s_add_u32 s38, s38, 0x40000
	s_addc_u32 s39, s39, 0
	s_mov_b32 m0, s54
	v_lshl_add_u64 v[246:247], s[38:39], 0, v[186:187]
	ds_read_b128 v[160:163], v230 offset:32768
	ds_read_b128 v[164:167], v230 offset:33792
	ds_read_b128 v[168:171], v230 offset:34816
	ds_read_b128 v[192:195], v230 offset:35840
	ds_read_b128 v[196:199], v230 offset:36864
	ds_read_b128 v[200:203], v230 offset:37888
	ds_read_b128 v[204:207], v230 offset:38912
	ds_read_b128 v[236:239], v230 offset:39936
	global_load_lds_dwordx4 v[246:247], off
	v_lshl_add_u64 v[246:247], s[38:39], 0, v[184:185]
	s_mov_b32 m0, s55
	s_nop 0
	global_load_lds_dwordx4 v[246:247], off
	s_waitcnt vmcnt(8)
	s_waitcnt lgkmcnt(0)
	s_barrier
	s_setprio 1
	s_waitcnt lgkmcnt(0)
	v_mfma_f32_16x16x32_bf16 v[140:143], v[68:71], v[160:163], v[140:143]
	v_mfma_f32_16x16x32_bf16 v[136:139], v[80:83], v[160:163], v[136:139]
	v_mfma_f32_16x16x32_bf16 v[124:127], v[68:71], v[168:171], v[124:127]
	v_mfma_f32_16x16x32_bf16 v[120:123], v[80:83], v[168:171], v[120:123]
	v_mfma_f32_16x16x32_bf16 v[108:111], v[68:71], v[196:199], v[108:111]
	v_mfma_f32_16x16x32_bf16 v[104:107], v[80:83], v[196:199], v[104:107]
	v_mfma_f32_16x16x32_bf16 v[92:95], v[68:71], v[204:207], v[92:95]
	v_mfma_f32_16x16x32_bf16 v[88:91], v[80:83], v[204:207], v[88:91]
	v_mfma_f32_16x16x32_bf16 v[140:143], v[72:75], v[164:167], v[140:143]
	v_mfma_f32_16x16x32_bf16 v[136:139], v[84:87], v[164:167], v[136:139]
	v_mfma_f32_16x16x32_bf16 v[124:127], v[72:75], v[192:195], v[124:127]
	v_mfma_f32_16x16x32_bf16 v[120:123], v[84:87], v[192:195], v[120:123]
	v_mfma_f32_16x16x32_bf16 v[108:111], v[72:75], v[200:203], v[108:111]
	v_mfma_f32_16x16x32_bf16 v[104:107], v[84:87], v[200:203], v[104:107]
	v_mfma_f32_16x16x32_bf16 v[92:95], v[72:75], v[236:239], v[92:95]
	v_mfma_f32_16x16x32_bf16 v[88:91], v[84:87], v[236:239], v[88:91]
	s_setprio 0
	s_setprio 1
	v_mfma_f32_16x16x32_bf16 v[132:135], v[144:147], v[160:163], v[132:135]
	v_mfma_f32_16x16x32_bf16 v[128:131], v[152:155], v[160:163], v[128:131]
	v_mfma_f32_16x16x32_bf16 v[116:119], v[144:147], v[168:171], v[116:119]
	v_mfma_f32_16x16x32_bf16 v[112:115], v[152:155], v[168:171], v[112:115]
	v_mfma_f32_16x16x32_bf16 v[100:103], v[144:147], v[196:199], v[100:103]
	v_mfma_f32_16x16x32_bf16 v[96:99], v[152:155], v[196:199], v[96:99]
	v_mfma_f32_16x16x32_bf16 v[76:79], v[144:147], v[204:207], v[76:79]
	v_mfma_f32_16x16x32_bf16 v[64:67], v[152:155], v[204:207], v[64:67]
	s_setprio 2
	s_barrier
; #define PG8_STAGE(bufoff, gbase, voff) do { _Pragma("unroll") for (int _i = 0; _i < 2; ++_i) \
;         __builtin_amdgcn_global_load_lds((const unsigned*)((const char*)(gbase) + (voff)[_i]), (PG8_LAS unsigned*)(lds + (bufoff) + ldsw + _i * 8192), 16, 0, 0); } while (0)
; #define PG8_LDA(dst, b, h) do { _Pragma("unroll") for (int m = 0; m < 4; ++m) _Pragma("unroll") for (int k = 0; k < 2; ++k) dst[m][k] = *(const PG8_LAS bf16x8*)(lds + PG8_SA(b, h) + aoff + m * 2048 + k * 1024); } while (0)
; #define PG8_MMA(ai, bj, At, Bt) do { __builtin_amdgcn_s_setprio(1); _Pragma("unroll") for (int m = 0; m < 4; ++m) _Pragma("unroll") for (int n = 0; n < 2; ++n) _Pragma("unroll") for (int k = 0; k < 2; ++k) \
;         acc[ai][bj][m][n] = __builtin_amdgcn_mfma_f32_16x16x32_bf16(Bt[n][k], At[m][k], acc[ai][bj][m][n], 0, 0, 0); __builtin_amdgcn_s_setprio(0); } while (0)
; #define PG8_WAIT_V(n) asm volatile("s_waitcnt vmcnt(" #n ")" ::: "memory")
; #define PG8_WAIT_L(n) asm volatile("s_waitcnt lgkmcnt(" #n ")" ::: "memory")
; #define PG8_BAR __builtin_amdgcn_s_barrier()
; #define PG8_SCHED __builtin_amdgcn_sched_barrier(0)
; template <class Epi, class Sched, bool ALIGN_EPI = false, bool SP2 = false>
; __device__ __forceinline__ void gemm_phase(PG8_LAS unsigned char* lds, const Gemm g, const Sched& S, const Epi& E) {
;     ...
;             PG8_WAIT_V(8); PG8_WAIT_L(0); PG8_BAR; PG8_MMA(0, 0, At, B0); PG8_MMA(0, 1, At, B1); PG8_BAR; PG8_SCHED;
;             PG8_LDA(At, 1, 1); PG8_STAGE(PG8_SB(1, 0), b3, voffB); PG8_STAGE(PG8_SB(1, 1), b3 + hstep, voffB); PG8_STAGE(PG8_SA(1, 0), a3, voffA);
;             PG8_WAIT_V(8); PG8_WAIT_L(0); PG8_BAR; PG8_MMA(1, 0, At, B0); PG8_MMA(1, 1, At, B1); PG8_BAR; PG8_SCHED;
;     ...
;         }
;         if constexpr (ALIGN_EPI) { if (wr == 0) PG8_BAR; }
	v_mfma_f32_16x16x32_bf16 v[132:135], v[148:151], v[164:167], v[132:135]
	v_mfma_f32_16x16x32_bf16 v[128:131], v[156:159], v[164:167], v[128:131]
	v_mfma_f32_16x16x32_bf16 v[116:119], v[148:151], v[192:195], v[116:119]
	v_mfma_f32_16x16x32_bf16 v[112:115], v[156:159], v[192:195], v[112:115]
	v_mfma_f32_16x16x32_bf16 v[100:103], v[148:151], v[200:203], v[100:103]
	v_mfma_f32_16x16x32_bf16 v[96:99], v[156:159], v[200:203], v[96:99]
	v_mfma_f32_16x16x32_bf16 v[76:79], v[148:151], v[236:239], v[76:79]
	v_mfma_f32_16x16x32_bf16 v[64:67], v[156:159], v[236:239], v[64:67]
	s_setprio 0
	s_add_i32 s38, s68, s45
	v_lshl_add_u64 v[210:211], v[210:211], 0, s[88:89]
	s_mov_b32 m0, s38
	ds_read_b128 v[160:163], v230 offset:49152
	ds_read_b128 v[164:167], v230 offset:50176
	ds_read_b128 v[168:171], v230 offset:51200
	ds_read_b128 v[192:195], v230 offset:52224
	ds_read_b128 v[196:199], v230 offset:53248
	ds_read_b128 v[200:203], v230 offset:54272
	ds_read_b128 v[204:207], v230 offset:55296
	ds_read_b128 v[236:239], v230 offset:56320
	global_load_lds_dwordx4 v[210:211], off
	s_add_i32 m0, s38, 0x2000
	s_add_u32 s36, s36, 0x40080
	v_lshl_add_u64 v[210:211], v[240:241], 0, s[88:89]
	s_addc_u32 s37, s37, 0
	s_add_i32 s38, s69, s45
	global_load_lds_dwordx4 v[210:211], off
	v_lshl_add_u64 v[210:211], s[36:37], 0, v[172:173]
	s_mov_b32 m0, s38
	s_nop 0
	global_load_lds_dwordx4 v[210:211], off
	v_lshl_add_u64 v[210:211], s[36:37], 0, v[182:183]
	s_add_i32 m0, s38, 0x2000
	s_nop 0
	global_load_lds_dwordx4 v[210:211], off
	v_lshl_add_u64 v[210:211], v[242:243], 0, s[88:89]
	s_mov_b32 m0, s56
	s_nop 0
	global_load_lds_dwordx4 v[210:211], off
	v_lshl_add_u64 v[210:211], v[244:245], 0, s[88:89]
	s_mov_b32 m0, s57
	s_nop 0
	global_load_lds_dwordx4 v[210:211], off
	s_waitcnt vmcnt(8)
	s_waitcnt lgkmcnt(0)
	s_barrier
	s_setprio 1
	s_waitcnt lgkmcnt(0)
	v_mfma_f32_16x16x32_bf16 v[60:63], v[68:71], v[160:163], v[60:63]
	v_mfma_f32_16x16x32_bf16 v[56:59], v[80:83], v[160:163], v[56:59]
	v_mfma_f32_16x16x32_bf16 v[44:47], v[68:71], v[168:171], v[44:47]
	v_mfma_f32_16x16x32_bf16 v[40:43], v[80:83], v[168:171], v[40:43]
	v_mfma_f32_16x16x32_bf16 v[28:31], v[68:71], v[196:199], v[28:31]
	v_mfma_f32_16x16x32_bf16 v[24:27], v[80:83], v[196:199], v[24:27]
	v_mfma_f32_16x16x32_bf16 v[12:15], v[68:71], v[204:207], v[12:15]
	v_mfma_f32_16x16x32_bf16 v[8:11], v[80:83], v[204:207], v[8:11]
	v_mfma_f32_16x16x32_bf16 v[60:63], v[72:75], v[164:167], v[60:63]
	v_mfma_f32_16x16x32_bf16 v[56:59], v[84:87], v[164:167], v[56:59]
	v_mfma_f32_16x16x32_bf16 v[44:47], v[72:75], v[192:195], v[44:47]
	v_mfma_f32_16x16x32_bf16 v[40:43], v[84:87], v[192:195], v[40:43]
	v_mfma_f32_16x16x32_bf16 v[28:31], v[72:75], v[200:203], v[28:31]
	v_mfma_f32_16x16x32_bf16 v[24:27], v[84:87], v[200:203], v[24:27]
	v_mfma_f32_16x16x32_bf16 v[12:15], v[72:75], v[236:239], v[12:15]
	v_mfma_f32_16x16x32_bf16 v[8:11], v[84:87], v[236:239], v[8:11]
	s_setprio 0
	s_setprio 1
	v_mfma_f32_16x16x32_bf16 v[52:55], v[144:147], v[160:163], v[52:55]
	v_mfma_f32_16x16x32_bf16 v[48:51], v[152:155], v[160:163], v[48:51]
	v_mfma_f32_16x16x32_bf16 v[36:39], v[144:147], v[168:171], v[36:39]
	v_mfma_f32_16x16x32_bf16 v[32:35], v[152:155], v[168:171], v[32:35]
	v_mfma_f32_16x16x32_bf16 v[20:23], v[144:147], v[196:199], v[20:23]
	v_mfma_f32_16x16x32_bf16 v[16:19], v[152:155], v[196:199], v[16:19]
	v_mfma_f32_16x16x32_bf16 v[4:7], v[144:147], v[204:207], v[4:7]
	v_mfma_f32_16x16x32_bf16 v[0:3], v[152:155], v[204:207], v[0:3]
	s_setprio 2
	s_barrier
	v_mfma_f32_16x16x32_bf16 v[52:55], v[148:151], v[164:167], v[52:55]
	v_mfma_f32_16x16x32_bf16 v[48:51], v[156:159], v[164:167], v[48:51]
	v_mfma_f32_16x16x32_bf16 v[36:39], v[148:151], v[192:195], v[36:39]
	v_mfma_f32_16x16x32_bf16 v[32:35], v[156:159], v[192:195], v[32:35]
	v_mfma_f32_16x16x32_bf16 v[20:23], v[148:151], v[200:203], v[20:23]
	v_mfma_f32_16x16x32_bf16 v[16:19], v[156:159], v[200:203], v[16:19]
	v_mfma_f32_16x16x32_bf16 v[4:7], v[148:151], v[236:239], v[4:7]
	v_mfma_f32_16x16x32_bf16 v[0:3], v[156:159], v[236:239], v[0:3]
	s_setprio 0
	s_add_i32 s67, s67, 2
	s_add_u32 s34, s34, 0x100
	s_addc_u32 s35, s35, 0
	s_add_u32 s65, s65, 0x100
	s_addc_u32 s66, s66, 0
	s_cmp_gt_u32 s67, 13
	s_cbranch_scc0 .LBB0_613
	s_and_b64 vcc, exec, s[22:23]
	s_cbranch_vccz .LBB0_616
	s_barrier
